# static s_setprio 1 for waves 4-7 through the attention phases
# speedup vs baseline: 1.0005x; 1.0005x over previous
; template <int KW, int DQK, int DV>
; DI void attn_dense_pair(LAS unsigned char* lds, const int tid, const bf16_t* Qw, int qpitch, const bf16_t* Kb, int kpitch, const bf16_t* Vb, int vpitch,
;                         float nbound, f32x16 (&o)[DV / 32], float& l_out) {
;     ...
;     const int lane = tid & 63, r32 = lane & 31, hi = lane >> 5;
;     bf16x8 qf[DQK / 16];
; #pragma unroll
;     for (int d0 = 0; d0 < DQK / 16; ++d0) qf[d0] = *(const bf16x8*)(Qw + (size_t)r32 * qpitch + d0 * 16 + hi * 8);
;     u32x4 kreg[2][KPT], vreg[2][VPT];
;     unsigned kgo[KPT], klo[KPT], vgo[VPT], vlo[VPT];
; #pragma unroll
;     for (int i_ = 0; i_ < KPT; ++i_) { const int c_ = tid + i_ * 512; const int key_ = c_ / KCH, part_ = c_ % KCH; kgo[i_] = (unsigned)(key_ * kpitch + part_ * 8) * 2u; klo[i_] = (unsigned)(key_ * KP + part_ * 16); }
; #pragma unroll
;     for (int i_ = 0; i_ < VPT; ++i_) { const int c_ = tid + i_ * 512; const int key_ = c_ / VCH, part_ = c_ % VCH; vgo[i_] = (unsigned)(key_ * vpitch + part_ * 8) * 2u; vlo[i_] = (unsigned)(4 * KT + key_ * VP + part_ * 16); }
;     const bool kact1 = (NKC % 512 == 0) || (tid + (KPT - 1) * 512 < NKC);
;     constexpr int NT = S / 64;
;     ...
; #pragma unroll
;     for (int d0 = 0; d0 < DV / 32; ++d0)
; #pragma unroll
;         for (int r = 0; r < 16; ++r) o[d0][r] = 0.f;
;     const int koff = r32 * KP + hi * 16;
;     const int voff = 4 * KT + (4 * hi + ((lane & 15) >> 2)) * VP + (((lane >> 4) & 1) * 16 + (lane & 3) * 4) * 2;
;     { u32x4 kreg0[KPT];
;       { const char* kt_ = (const char*)Kb;
;         _Pragma("unroll") for (int i_ = 0; i_ < KPT; ++i_) { if (i_ + 1 < KPT || kact1) kreg0[i_] = *(const u32x4*)(kt_ + kgo[i_]); } }
;       AP_GLOAD_K(0, 1); AP_GLOAD_K(1, 2); AP_GLOAD_V(0, 0); AP_GLOAD_V(1, 1);
;       _Pragma("unroll") for (int i_ = 0; i_ < KPT; ++i_) { if (i_ + 1 < KPT || kact1) *(LAS u32x4*)(lds + klo[i_]) = kreg0[i_]; } }
;     __syncthreads();
;     u32x4 pw[4];
;     { f32x16 pc0, pc1;
; #pragma unroll
;       for (int r = 0; r < 16; ++r) { pc0[r] = nbound; pc1[r] = nbound; }
;       qk_tile<DQK, KP>(pc0, pc1, lds + koff, qf);
;       exp_tile(pc0, pc1);
; DI float wave_absmax(const float* w, int n, int lane) {
;     float m = 0.f;
;     for (int i = lane; i < n; i += 64) m = fmaxf(m, fabsf(w[i]));
; #pragma unroll
;     for (int o = 1; o < 64; o <<= 1) m = fmaxf(m, shx(m, o, lane));
;     return m;
.LBB0_380:
	s_or_b64 exec, exec, s[2:3]
	ds_bpermute_b32 v1, v7, v4
	v_max_f32_e32 v2, v4, v4
	s_waitcnt lgkmcnt(1)
	v_max_f32_e32 v3, v14, v14
	v_max_f32_e32 v4, v12, v12
	v_max_f32_e32 v3, v4, v3
	s_waitcnt lgkmcnt(0)
	v_max_f32_e32 v1, v1, v1
	v_max_f32_e32 v1, v2, v1
	ds_bpermute_b32 v2, v8, v1
	v_mul_f32_e32 v3, 0xc13c5bb7, v3
	s_cmpk_gt_i32 s20, 0xff
	s_waitcnt lgkmcnt(0)
	v_max_f32_e32 v2, v2, v2
	v_max_f32_e32 v1, v1, v2
	ds_bpermute_b32 v2, v9, v1
	s_waitcnt lgkmcnt(0)
	v_max_f32_e32 v2, v2, v2
	v_max_f32_e32 v1, v1, v2
	ds_bpermute_b32 v2, v10, v1
	s_waitcnt lgkmcnt(0)
	v_max_f32_e32 v2, v2, v2
	v_max_f32_e32 v1, v1, v2
	ds_bpermute_b32 v2, v11, v1
	s_waitcnt lgkmcnt(0)
	v_max_f32_e32 v2, v2, v2
	v_max_f32_e32 v1, v1, v2
	ds_bpermute_b32 v2, v13, v1
	s_waitcnt lgkmcnt(0)
	v_max_f32_e32 v2, v2, v2
	v_max_f32_e32 v1, v1, v2
	v_mul_f32_e32 v1, v3, v1
	s_nop 0
	v_readfirstlane_b32 s48, v1
	s_cbranch_scc1 .LBB0_385
	s_cmp_lt_u32 s14, 4
	s_cbranch_scc1 .Lprio_attn_skip
	s_setprio 1
.Lprio_attn_skip:
	v_lshl_add_u32 v1, s14, 6, v0
	v_ashrrev_i32_e32 v6, 31, v1
	v_lshrrev_b32_e32 v6, 29, v6
	v_add_u32_e32 v6, v1, v6
	s_add_u32 s2, s26, s6
	v_ashrrev_i32_e32 v7, 3, v6
	v_and_b32_e32 v6, 0xffffff8, v6
	s_addc_u32 s3, s27, s7
	v_sub_u32_e32 v6, v1, v6
	v_mul_lo_u32 v9, v7, s68
	s_add_u32 s10, s2, 0x2d800000
	v_bfe_u32 v4, v0, 5, 1
	v_lshl_add_u32 v168, v6, 4, v9
	v_bfe_u32 v6, v0, 2, 2
	s_addc_u32 s11, s3, 0
	v_and_b32_e32 v2, 63, v0
	v_and_b32_e32 v3, 31, v0
	v_lshlrev_b32_e32 v18, 3, v4
	v_add_u32_e32 v8, v7, v1
	v_lshlrev_b32_e32 v166, 4, v1
	v_lshlrev_b32_e32 v1, 4, v4
	v_lshl_or_b32 v4, v4, 2, v6
	v_and_b32_e32 v0, 16, v0
	s_add_u32 s16, s2, 0x2e000000
	v_mul_u32_u24_e32 v4, 0xc0, v4
	v_and_or_b32 v0, v5, 12, v0
	s_addc_u32 s17, s3, 0
	v_lshl_or_b32 v0, v0, 1, v4
	v_mul_u32_u24_e32 v4, 0x90, v3
	s_mov_b32 s0, 0xffff74c0
	s_add_u32 s4, s2, 0x32200000
	v_add3_u32 v183, v1, v4, 0
	v_mul_lo_u32 v1, v7, s0
	s_addc_u32 s5, s3, 0
	s_lshl_b32 s21, s14, 5
	v_add3_u32 v184, v168, v1, 0
	v_cmp_eq_u32_e32 vcc, 0, v3
	v_mov_b32_e32 v1, 0x3f80
	s_add_u32 s30, s2, 0x18402a40
	v_cndmask_b32_e32 v1, 0, v1, vcc
	s_mov_b32 s0, 0x5040100
	s_addc_u32 s31, s3, 0
	v_perm_b32 v112, v1, v1, s0
	v_readlane_b32 s0, v254, 2
	s_add_u32 s0, s0, s6
	v_readlane_b32 s1, v254, 3
	v_mov_b32_e32 v169, v129
	s_addc_u32 s1, s1, s7
	v_lshl_add_u64 v[170:171], s[0:1], 0, v[168:169]
	v_readlane_b32 s0, v254, 4
	s_mov_b32 s49, s48
	v_or_b32_e32 v17, 0x9000, v0
	v_add_u32_e32 v185, 0, v0
	v_lshlrev_b32_e32 v0, 2, v2
	s_add_u32 s0, s0, s6
	v_readlane_b32 s1, v254, 5
	v_lshlrev_b32_e32 v16, 6, v3
	v_mov_b32_e32 v167, v129
	v_lshl_add_u32 v182, v8, 4, 0
	s_mov_b32 s50, s48
	s_mov_b32 s51, s48
	s_mov_b32 s52, s48
	s_mov_b32 s53, s48
	s_mov_b32 s54, s48
	s_mov_b32 s55, s48
	s_mov_b32 s56, s48
	s_mov_b32 s57, s48
	s_mov_b32 s58, s48
	s_mov_b32 s59, s48
	s_mov_b32 s60, s48
	s_mov_b32 s61, s48
	s_mov_b32 s62, s48
	s_mov_b32 s63, s48
	v_xor_b32_e32 v191, 0x80, v0
	v_lshlrev_b32_e32 v192, 2, v3
	s_addc_u32 s1, s1, s7
	v_mov_b64_e32 v[0:1], s[48:49]
	v_mov_b32_e32 v113, v112
	v_mov_b32_e32 v114, v112
	v_mov_b32_e32 v115, v112
	v_add_u32_e32 v190, 0xf000, v185
	v_lshl_add_u64 v[172:173], s[0:1], 0, v[166:167]
	v_mov_b64_e32 v[2:3], s[50:51]
	v_mov_b64_e32 v[4:5], s[52:53]
	v_mov_b64_e32 v[6:7], s[54:55]
	v_mov_b64_e32 v[8:9], s[56:57]
	v_mov_b64_e32 v[10:11], s[58:59]
	v_mov_b64_e32 v[12:13], s[60:61]
	v_mov_b64_e32 v[14:15], s[62:63]
	v_add_u32_e32 v193, 0, v17
	v_lshlrev_b32_e32 v128, 1, v16
	v_lshlrev_b32_e32 v174, 1, v18
